# phase A tile walk: the two per-tile reciprocal computations (VALU rcp + readfirstlane chains) replaced by selected constant magic numbers
# speedup vs baseline: 1.0044x; 1.0044x over previous
;   DI bool next(int& mt, int& nt) {
;     if (L >= total) return false;
;     if (x < 0) { mt = L / NT; nt = L % NT; L += step; return true; }
;     const int colsz = mx * 8;
;     const int nfull = NT >> 3;
;     int ng = L / colsz, gn = 8;
;     if (ng >= nfull) { ng = nfull; gn = NT & 7; }
;     const int Lp = L - ng * colsz;
;     const int mg = Lp / (8 * gn), r = Lp - mg * 8 * gn;
;     const int rows = (mx - 8 * mg) < 8 ? (mx - 8 * mg) : 8;
;     const int lm = r / gn, ln = r - lm * gn;
;     mt = (8 * mg + lm) * 8 + x; nt = ng * 8 + ln;
;     L += step;
.LBB0_1185:
	s_cmp_lt_i32 s51, s52
	s_cselect_b64 s[0:1], -1, 0
	s_cmp_ge_i32 s51, s52
	s_cbranch_scc1 .LBB0_1191
	s_mov_b64 s[4:5], -1
	s_and_b64 vcc, exec, s[8:9]
	s_cbranch_vccz .LBB0_1188
	s_abs_i32 s5, s51
	s_mul_hi_u32 s10, s5, s54
	s_mul_i32 s11, s10, s53
	s_sub_i32 s5, s5, s11
	s_ashr_i32 s4, s51, 31
	s_add_i32 s11, s10, 1
	s_sub_i32 s12, s5, s53
	s_cmp_ge_u32 s5, s53
	s_cselect_b32 s10, s11, s10
	s_cselect_b32 s5, s12, s5
	s_add_i32 s11, s10, 1
	s_cmp_ge_u32 s5, s53
	s_cselect_b32 s5, s11, s10
	s_xor_b32 s5, s5, s4
	s_sub_i32 s4, s5, s4
	s_cmp_lt_i32 s4, 5
	s_cselect_b32 s10, 8, 3
	s_cselect_b32 s5, -8, -3
	s_mov_b32 s16, 0xaaaaaaa
	s_cselect_b32 s16, 0x4000000, s16
	s_mov_b32 s98, 0x55555555
	s_cselect_b32 s98, 0x20000000, s98
	s_lshl_b32 s11, s10, 3
	s_min_i32 s4, s4, 5
	s_mul_i32 s12, s4, s53
	s_sub_i32 s12, s51, s12
	s_abs_i32 s14, s12
	s_ashr_i32 s13, s12, 31
	s_mul_hi_u32 s15, s14, s16
	s_mul_i32 s16, s15, s11
	s_sub_i32 s14, s14, s16
	s_add_i32 s16, s15, 1
	s_sub_i32 s17, s14, s11
	s_cmp_ge_u32 s14, s11
	s_cselect_b32 s15, s16, s15
	s_cselect_b32 s14, s17, s14
	s_add_i32 s16, s15, 1
	s_cmp_ge_u32 s14, s11
	s_cselect_b32 s11, s16, s15
	s_xor_b32 s11, s11, s13
	s_sub_i32 s11, s11, s13
	s_lshl_b32 s11, s11, 3
	s_mul_i32 s13, s11, s10
	s_sub_i32 s12, s12, s13
	s_abs_i32 s14, s12
	s_mov_b32 s16, s98
	s_mul_hi_u32 s15, s14, s16
	s_mul_i32 s16, s15, s10
	s_sub_i32 s14, s14, s16
	s_ashr_i32 s13, s12, 31
	s_add_i32 s16, s15, 1
	s_sub_i32 s17, s14, s10
	s_cmp_ge_u32 s14, s10
	s_cselect_b32 s15, s16, s15
	s_cselect_b32 s14, s17, s14
	s_add_i32 s16, s15, 1
	s_cmp_ge_u32 s14, s10
	s_cselect_b32 s10, s16, s15
	s_xor_b32 s10, s10, s13
	s_sub_i32 s10, s10, s13
	s_mul_i32 s5, s5, s10
	s_add_i32 s11, s11, s10
	s_lshl_b32 s4, s4, 3
	s_lshl_b32 s10, s11, 3
	s_add_i32 s4, s5, s4
	s_add_i32 s36, s10, s49
	s_add_i32 s37, s4, s12
	s_mov_b64 s[4:5], 0
